# s10 + xb_helper1: at the P1->P2 barrier the first workgroup of each XCD to arrive also starts an L2 write-back (un-waited), so the leader's final write-back has less to drain
# baseline (speedup 1.0000x reference)
.Lxb_nh_1:
	v_readfirstlane_b32 s9, v2
	s_sub_i32 s11, s11, s9
	s_add_i32 s11, s11, 1
	s_cmp_lg_u32 s10, s11
	s_cbranch_scc1 .Lxb_nl_1
	buffer_wbl2 sc1
